# grid barrier: the XCD leader issues its acquire invalidate right after its arrival increment instead of before the release write-back (off the release critical path)
# speedup vs baseline: 1.0054x; 1.0054x over previous
; DI unsigned xb_add(unsigned* p, unsigned v) { return __hip_atomic_fetch_add(p, v, __ATOMIC_RELAXED, __HIP_MEMORY_SCOPE_AGENT); }
; DI void xcd_barrier(const XcdBarrier& b) {
;     ...
;       __builtin_amdgcn_fence(__ATOMIC_RELEASE, "agent");
;       asm volatile("s_waitcnt vmcnt(0)" ::: "memory");
;       const unsigned og = xb_add(&bar[XB_TOP], 1u);
.LBB0_293:
	s_andn2_saveexec_b64 s[2:3], s[12:13]
	s_cbranch_execz .LBB0_313
	s_mov_b64 s[12:13], exec
	buffer_wbl2 sc1
	s_waitcnt lgkmcnt(0)
	s_waitcnt vmcnt(0)
	v_mbcnt_lo_u32_b32 v3, s12, 0
	v_mbcnt_hi_u32_b32 v3, s13, v3
	v_cmp_eq_u32_e32 vcc, 0, v3
	s_and_saveexec_b64 s[14:15], vcc
	s_cbranch_execz .LBB0_296
	s_bcnt1_i32_b64 s2, s[12:13]
	v_mov_b32_e32 v4, s2
	v_mov_b32_e32 v5, 0xfc9f000
	global_atomic_add v4, v5, v4, s[8:9] offset:1024 sc0
	buffer_inv sc1

; DI unsigned xb_add(unsigned* p, unsigned v) { return __hip_atomic_fetch_add(p, v, __ATOMIC_RELAXED, __HIP_MEMORY_SCOPE_AGENT); }
; DI void xcd_barrier(const XcdBarrier& b) {
;     ...
;       __builtin_amdgcn_fence(__ATOMIC_RELEASE, "agent");
;       asm volatile("s_waitcnt vmcnt(0)" ::: "memory");
;       const unsigned og = xb_add(&bar[XB_TOP], 1u);
.LBB0_1833:
	s_andn2_saveexec_b64 s[2:3], s[16:17]
	s_cbranch_execz .LBB0_1853
	s_mov_b64 s[16:17], exec
	buffer_wbl2 sc1
	s_waitcnt lgkmcnt(0)
	s_waitcnt vmcnt(0)
	v_mbcnt_lo_u32_b32 v3, s16, 0
	v_mbcnt_hi_u32_b32 v3, s17, v3
	v_cmp_eq_u32_e32 vcc, 0, v3
	s_and_saveexec_b64 s[18:19], vcc
	s_cbranch_execz .LBB0_1836
	s_bcnt1_i32_b64 s2, s[16:17]
	v_mov_b32_e32 v4, s2
	v_mov_b32_e32 v5, 0xfc9f000
	global_atomic_add v4, v5, v4, s[12:13] offset:1024 sc0
	buffer_inv sc1

; DI unsigned xb_add(unsigned* p, unsigned v) { return __hip_atomic_fetch_add(p, v, __ATOMIC_RELAXED, __HIP_MEMORY_SCOPE_AGENT); }
; DI void xcd_barrier(const XcdBarrier& b) {
;     ...
;       __builtin_amdgcn_fence(__ATOMIC_RELEASE, "agent");
;       asm volatile("s_waitcnt vmcnt(0)" ::: "memory");
;       const unsigned og = xb_add(&bar[XB_TOP], 1u);
.LBB0_2054:
	s_mov_b64 s[12:13], exec
	buffer_wbl2 sc1
	s_waitcnt lgkmcnt(0)
	s_waitcnt vmcnt(0)
	v_mbcnt_lo_u32_b32 v3, s12, 0
	v_mbcnt_hi_u32_b32 v3, s13, v3
	v_cmp_eq_u32_e32 vcc, 0, v3
	s_and_saveexec_b64 s[14:15], vcc
	s_cbranch_execz .LBB0_2056
	s_bcnt1_i32_b64 s2, s[12:13]
	v_mov_b32_e32 v4, s2
	v_mov_b32_e32 v5, 0xfc9f000
	global_atomic_add v4, v5, v4, s[8:9] offset:1024 sc0
	buffer_inv sc1
